# sbpoll: grid-barrier wait keeps two polls of the seam word in flight (staggered, destinations v239/v248 freed by re-materialising their constants), iteration cap instead of the sticky timeout words (o
# baseline (speedup 1.0000x reference)
.LBB0_6:
	s_load_dword s3, s[26:27], 0xf0
	s_mul_i32 s2, s47, s46
	s_cmpk_lt_i32 s59, 0x1001
	v_lshrrev_b32_e32 v1, 20, v0
	v_lshrrev_b32_e32 v0, 10, v0
	s_waitcnt lgkmcnt(0)
	s_mul_i32 s79, s2, s3
	s_cselect_b64 s[2:3], -1, 0
	v_writelane_b32 v254, s2, 2
	v_or_b32_e32 v0, v0, v1
	v_mov_b32_e32 v1, 0
	v_writelane_b32 v254, s3, 3
	s_lshl_b32 s2, s6, 6
	v_writelane_b32 v254, s2, 4
	s_lshl_b32 s2, s6, 8
	s_add_u32 s0, s0, s2
	s_addc_u32 s1, s1, 0
	v_writelane_b32 v254, s0, 5
	s_mov_b32 s86, 0x800000
	s_movk_i32 s85, 0x1400
	v_writelane_b32 v254, s1, 6
	s_add_u32 s0, s56, 0xf500200
	s_addc_u32 s1, s57, 0
	v_writelane_b32 v254, s0, 7
	s_add_u32 s84, s56, 0xf500400
	s_addc_u32 s57, s57, 0
	v_writelane_b32 v254, s1, 8
	s_movk_i32 s0, 0x3ff
	v_and_or_b32 v0, v0, s0, v244
	s_add_i32 s0, 0, 0x1f000
	v_writelane_b32 v254, s0, 9
	s_add_i32 s0, 0, 0x14c00
	v_writelane_b32 v254, s0, 10
	s_add_i32 s0, 0, 0x23fc0
	v_writelane_b32 v254, s0, 11
	s_add_i32 s0, 0, 0x23fc4
	v_writelane_b32 v254, s0, 12
	v_cmp_eq_u32_e64 s[0:1], 0, v0
	s_movk_i32 s88, 0x110
	s_movk_i32 s89, 0x90
	v_writelane_b32 v254, s0, 13
	v_mov_b32_e32 v218, 0x358637bd
	s_mov_b32 s73, 0xf700000
	v_writelane_b32 v254, s1, 14
	v_writelane_b32 v254, s26, 15
	s_mov_b32 s0, s46
	s_mov_b32 s87, 0x9000
	v_writelane_b32 v254, s27, 16
	v_writelane_b32 v254, s0, 17
	s_movk_i32 s33, 0x101
	s_mov_b32 s66, 0xf149f2ca
	v_writelane_b32 v254, s1, 18
	v_writelane_b32 v254, s22, 19
	s_movk_i32 s67, 0xfefe
	s_movk_i32 s90, 0x800
	v_mov_b32_e32 v242, 0x3ecc95a3
	s_mov_b32 s45, 0x12000
	s_movk_i32 s54, 0x1600
	v_mov_b32_e32 v240, 0xbab64f3b
	v_mov_b32_e32 v246, 0x1000
	v_mov_b32_e32 v238, 0x1400
	v_mov_b32_e32 v243, 0xf149f2ca
	v_mov_b32_e32 v219, 0x7f800000
	v_mov_b32_e32 v245, 0x7fc00000
	v_mov_b32_e32 v247, 1
	v_mov_b64_e32 v[252:253], 0x1e8481
	v_not_b32_e32 v249, 31
	s_mov_b32 s38, 0x63000
	s_mov_b32 s39, 0xc6000
	s_mov_b32 s91, 0x129000
	s_movk_i32 s55, 0x5800
	s_mov_b32 s72, 0x24000
	s_movk_i32 s63, 0x9ff
	s_mov_b32 s56, 0x3e38aa3b
	s_mov_b64 s[74:75], 0x100
	s_mov_b64 s[76:77], 0x80
	s_mov_b32 s81, 0
	s_mov_b64 s[70:71], 0x800
	v_writelane_b32 v254, s23, 20
	s_branch .LBB0_11

.LBB0_1062:
	s_or_b64 exec, exec, s[8:9]
	v_mul_f32_e32 v0, v13, v13
	v_mov_b32_e32 v10, 0x3c0881c4
	v_fmac_f32_e32 v10, 0xb94c1982, v0
	v_fmaak_f32 v10, v0, v10, 0xbe2aaa9d
	v_mul_f32_e32 v10, v0, v10
	v_fmac_f32_e32 v13, v13, v10
	v_fmamk_f32 v10, v0, 0x37d75334, v240
	v_fmaak_f32 v10, v0, v10, 0x3d2aabf7
	v_fmaak_f32 v10, v0, v10, 0xbf000004
	v_fma_f32 v0, v0, v10, 1.0
	v_and_b32_e32 v10, 1, v12
	v_cmp_eq_u32_e32 vcc, 0, v10
	v_lshlrev_b32_e32 v10, 30, v12
	v_and_b32_e32 v10, 0x80000000, v10
	v_xor_b32_e32 v8, v9, v8
	v_cndmask_b32_e32 v0, v0, v13, vcc
	v_xor_b32_e32 v8, v8, v10
	v_xor_b32_e32 v0, v8, v0
	v_cndmask_b32_e64 v0, v245, v0, s[6:7]
	s_movk_i32 s6, 0x5ff
	global_store_dword v[4:5], v0, off
	v_add_u32_e32 v0, 0x200, v7
	v_cmp_lt_i32_e32 vcc, s6, v7
	v_lshl_add_u64 v[4:5], v[4:5], 0, s[70:71]
	s_or_b64 s[4:5], vcc, s[4:5]
	v_mov_b32_e32 v7, v0
	s_andn2_b64 exec, exec, s[4:5]
	s_cbranch_execz .LBB0_1071
.LBB0_1063:
	v_ashrrev_i32_e32 v0, 4, v7
	v_cvt_f32_i32_e32 v0, v0
	s_brev_b32 s6, 18
	v_mul_f32_e32 v8, v6, v0
	v_and_b32_e32 v9, 0x7fffffff, v8
	v_lshrrev_b32_e32 v0, 23, v9
	v_and_b32_e32 v10, 0x7fffff, v9
	v_cmp_nlt_f32_e64 s[12:13], |v8|, s6
	v_add_u32_e32 v11, 0xffffff88, v0
	v_or_b32_e32 v10, 0x800000, v10
	s_and_saveexec_b64 s[6:7], s[12:13]
	s_xor_b64 s[14:15], exec, s[6:7]
	s_cbranch_execz .LBB0_1065
	v_cmp_lt_u32_e32 vcc, 63, v11
	s_nop 1
	v_cndmask_b32_e64 v0, 0, -1, vcc
	v_lshlrev_b32_e32 v0, 6, v0
	v_add_u32_e32 v0, v0, v11
	v_cmp_lt_u32_e64 s[6:7], 31, v0
	s_nop 1
	v_cndmask_b32_e64 v12, 0, v249, s[6:7]
	v_add_u32_e32 v0, v12, v0
	v_cmp_lt_u32_e64 s[8:9], 31, v0
	s_nop 1
	v_cndmask_b32_e64 v12, 0, v249, s[8:9]
	v_add_u32_e32 v26, v12, v0
	v_mad_u64_u32 v[12:13], s[10:11], v10, s18, 0
	v_mov_b32_e32 v0, v13
	v_mad_u64_u32 v[14:15], s[10:11], v10, s19, v[0:1]
	v_mov_b32_e32 v0, v15
	v_mad_u64_u32 v[16:17], s[10:11], v10, s20, v[0:1]
	v_mov_b32_e32 v0, v17
	v_mad_u64_u32 v[18:19], s[10:11], v10, s21, v[0:1]
	v_mov_b32_e32 v0, v19
	v_mad_u64_u32 v[20:21], s[10:11], v10, s24, v[0:1]
	v_mov_b32_e32 v0, v21
	v_mad_u64_u32 v[22:23], s[10:11], v10, s25, v[0:1]
	v_mov_b32_e32 v0, v23
	v_mad_u64_u32 v[24:25], s[10:11], v10, s28, v[0:1]
	v_cndmask_b32_e32 v13, v22, v18, vcc
	v_cndmask_b32_e32 v0, v24, v20, vcc
	v_cndmask_b32_e32 v17, v25, v22, vcc
	v_cndmask_b32_e64 v15, v0, v13, s[6:7]
	v_cndmask_b32_e64 v0, v17, v0, s[6:7]
	v_cndmask_b32_e32 v17, v20, v16, vcc
	v_cndmask_b32_e64 v13, v13, v17, s[6:7]
	v_cndmask_b32_e32 v14, v18, v14, vcc
	v_cndmask_b32_e64 v0, v0, v15, s[8:9]
	v_cndmask_b32_e64 v15, v15, v13, s[8:9]
	v_sub_u32_e32 v19, 32, v26
	v_cndmask_b32_e64 v17, v17, v14, s[6:7]
	v_alignbit_b32 v20, v0, v15, v19
	v_cmp_eq_u32_e64 s[10:11], 0, v26
	v_cndmask_b32_e64 v13, v13, v17, s[8:9]
	v_cndmask_b32_e32 v12, v16, v12, vcc
	v_cndmask_b32_e64 v0, v20, v0, s[10:11]
	v_alignbit_b32 v18, v15, v13, v19
	v_cndmask_b32_e64 v12, v14, v12, s[6:7]
	v_cndmask_b32_e64 v15, v18, v15, s[10:11]
	v_bfe_u32 v21, v0, 29, 1
	v_cndmask_b32_e64 v12, v17, v12, s[8:9]
	v_alignbit_b32 v18, v0, v15, 30
	v_sub_u32_e32 v22, 0, v21
	v_alignbit_b32 v14, v13, v12, v19
	v_xor_b32_e32 v18, v18, v22
	v_cndmask_b32_e64 v13, v14, v13, s[10:11]
	v_alignbit_b32 v14, v15, v13, 30
	v_ffbh_u32_e32 v15, v18
	v_min_u32_e32 v15, 32, v15
	v_alignbit_b32 v12, v13, v12, 30
	v_xor_b32_e32 v14, v14, v22
	v_sub_u32_e32 v16, 31, v15
	v_xor_b32_e32 v12, v12, v22
	v_alignbit_b32 v17, v18, v14, v16
	v_alignbit_b32 v12, v14, v12, v16
	v_alignbit_b32 v13, v17, v12, 9
	v_ffbh_u32_e32 v14, v13
	v_min_u32_e32 v14, 32, v14
	v_lshrrev_b32_e32 v20, 29, v0
	v_not_b32_e32 v16, v14
	v_alignbit_b32 v12, v13, v12, v16
	v_lshlrev_b32_e32 v13, 31, v20
	v_or_b32_e32 v16, 0x33000000, v13
	v_add_lshl_u32 v14, v14, v15, 23
	v_lshrrev_b32_e32 v12, 9, v12
	v_sub_u32_e32 v14, v16, v14
	v_or_b32_e32 v13, 0.5, v13
	v_lshlrev_b32_e32 v15, 23, v15
	v_or_b32_e32 v12, v14, v12
	v_lshrrev_b32_e32 v14, 9, v17
	v_sub_u32_e32 v13, v13, v15
	v_or_b32_e32 v13, v14, v13
	v_mul_f32_e32 v14, 0x3fc90fda, v13
	v_fma_f32 v15, v13, s29, -v14
	v_fmac_f32_e32 v15, 0x33a22168, v13
	v_fmac_f32_e32 v15, 0x3fc90fda, v12
	v_lshrrev_b32_e32 v0, 30, v0
	v_add_f32_e32 v13, v14, v15
	v_add_u32_e32 v12, v21, v0
.LBB0_1065:
	s_or_saveexec_b64 s[6:7], s[14:15]
	s_mov_b32 s8, 0x3f22f983
	v_mul_f32_e64 v0, |v8|, s8
	v_rndne_f32_e32 v0, v0
	s_xor_b64 exec, exec, s[6:7]
	v_cvt_i32_f32_e32 v12, v0
	v_fma_f32 v13, v0, s30, |v8|
	v_fmac_f32_e32 v13, 0xb3a22168, v0
	v_fmac_f32_e32 v13, 0xa7c234c4, v0
	s_or_b64 exec, exec, s[6:7]
	v_mul_f32_e32 v14, v13, v13
	v_mov_b32_e32 v15, 0x3c0881c4
	v_fmac_f32_e32 v15, 0xb94c1982, v14
	v_fmaak_f32 v15, v14, v15, 0xbe2aaa9d
	v_mul_f32_e32 v15, v14, v15
	v_fmac_f32_e32 v13, v13, v15
	v_fmamk_f32 v15, v14, 0x37d75334, v240
	v_fmaak_f32 v15, v14, v15, 0x3d2aabf7
	v_fmaak_f32 v15, v14, v15, 0xbf000004
	v_fma_f32 v14, v14, v15, 1.0
	v_and_b32_e32 v15, 1, v12
	v_cmp_eq_u32_e32 vcc, 0, v15
	v_lshlrev_b32_e32 v12, 30, v12
	s_brev_b32 s6, 1
	v_cndmask_b32_e64 v13, -v13, v14, vcc
	v_bitop3_b32 v12, v12, v13, s6 bitop3:0x6c
	s_movk_i32 s6, 0x1f8
	v_cmp_class_f32_e64 s[6:7], v8, s6
	s_nop 1
	v_cndmask_b32_e64 v14, v245, v12, s[6:7]
	v_add_co_u32_e32 v12, vcc, 0xffffe000, v4
	s_nop 1
	v_addc_co_u32_e32 v13, vcc, -1, v5, vcc
	global_store_dword v[12:13], v14, off
	s_and_saveexec_b64 s[8:9], s[12:13]
	s_xor_b64 s[14:15], exec, s[8:9]
	s_cbranch_execz .LBB0_1069
	v_cmp_lt_u32_e32 vcc, 63, v11
	v_mad_u64_u32 v[12:13], s[12:13], v10, s18, 0
	s_nop 0
	v_cndmask_b32_e64 v0, 0, -1, vcc
	v_lshlrev_b32_e32 v0, 6, v0
	v_add_u32_e32 v0, v0, v11
	v_cmp_lt_u32_e64 s[8:9], 31, v0
	s_nop 1
	v_cndmask_b32_e64 v11, 0, v249, s[8:9]
	v_add_u32_e32 v0, v11, v0
	v_cmp_lt_u32_e64 s[10:11], 31, v0
	s_nop 1
	v_cndmask_b32_e64 v11, 0, v249, s[10:11]
	v_add_u32_e32 v24, v11, v0
	v_mov_b32_e32 v0, v13
	v_mad_u64_u32 v[14:15], s[12:13], v10, s19, v[0:1]
	v_mov_b32_e32 v0, v15
	v_mad_u64_u32 v[16:17], s[12:13], v10, s20, v[0:1]
	v_mov_b32_e32 v0, v17
	v_mad_u64_u32 v[18:19], s[12:13], v10, s21, v[0:1]
	v_mov_b32_e32 v0, v19
	v_mad_u64_u32 v[20:21], s[12:13], v10, s24, v[0:1]
	v_mov_b32_e32 v0, v21
	v_mad_u64_u32 v[22:23], s[12:13], v10, s25, v[0:1]
	v_mov_b32_e32 v0, v23
	v_mad_u64_u32 v[10:11], s[12:13], v10, s28, v[0:1]
	v_cndmask_b32_e32 v13, v22, v18, vcc
	v_cndmask_b32_e32 v0, v10, v20, vcc
	v_cndmask_b32_e32 v11, v11, v22, vcc
	v_cndmask_b32_e64 v10, v0, v13, s[8:9]
	v_cndmask_b32_e64 v0, v11, v0, s[8:9]
	v_cndmask_b32_e32 v11, v20, v16, vcc
	v_cndmask_b32_e64 v13, v13, v11, s[8:9]
	v_cndmask_b32_e32 v14, v18, v14, vcc
	v_cndmask_b32_e64 v0, v0, v10, s[10:11]
	v_cndmask_b32_e64 v10, v10, v13, s[10:11]
	v_sub_u32_e32 v15, 32, v24
	v_cndmask_b32_e64 v11, v11, v14, s[8:9]
	v_alignbit_b32 v17, v0, v10, v15
	v_cmp_eq_u32_e64 s[12:13], 0, v24
	v_cndmask_b32_e64 v13, v13, v11, s[10:11]
	v_cndmask_b32_e32 v12, v16, v12, vcc
	v_cndmask_b32_e64 v0, v17, v0, s[12:13]
	v_alignbit_b32 v17, v10, v13, v15
	v_cndmask_b32_e64 v10, v17, v10, s[12:13]
	v_bfe_u32 v19, v0, 29, 1
	v_cndmask_b32_e64 v12, v14, v12, s[8:9]
	v_alignbit_b32 v17, v0, v10, 30
	v_sub_u32_e32 v20, 0, v19
	v_cndmask_b32_e64 v11, v11, v12, s[10:11]
	v_xor_b32_e32 v17, v17, v20
	v_alignbit_b32 v12, v13, v11, v15
	v_cndmask_b32_e64 v12, v12, v13, s[12:13]
	v_ffbh_u32_e32 v13, v17
	v_alignbit_b32 v10, v10, v12, 30
	v_min_u32_e32 v13, 32, v13
	v_alignbit_b32 v11, v12, v11, 30
	v_xor_b32_e32 v10, v10, v20
	v_sub_u32_e32 v14, 31, v13
	v_xor_b32_e32 v11, v11, v20
	v_alignbit_b32 v15, v17, v10, v14
	v_alignbit_b32 v10, v10, v11, v14
	v_alignbit_b32 v11, v15, v10, 9
	v_ffbh_u32_e32 v12, v11
	v_min_u32_e32 v12, 32, v12
	v_lshrrev_b32_e32 v18, 29, v0
	v_not_b32_e32 v14, v12
	v_alignbit_b32 v10, v11, v10, v14
	v_lshlrev_b32_e32 v11, 31, v18
	v_or_b32_e32 v14, 0x33000000, v11
	v_add_lshl_u32 v12, v12, v13, 23
	v_lshrrev_b32_e32 v10, 9, v10
	v_sub_u32_e32 v12, v14, v12
	v_or_b32_e32 v11, 0.5, v11
	v_lshlrev_b32_e32 v13, 23, v13
	v_or_b32_e32 v10, v12, v10
	v_lshrrev_b32_e32 v12, 9, v15
	v_sub_u32_e32 v11, v11, v13
	v_or_b32_e32 v11, v12, v11
	v_mul_f32_e32 v12, 0x3fc90fda, v11
	v_fma_f32 v13, v11, s29, -v12
	v_fmac_f32_e32 v13, 0x33a22168, v11
	v_fmac_f32_e32 v13, 0x3fc90fda, v10
	v_lshrrev_b32_e32 v0, 30, v0
	v_add_f32_e32 v13, v12, v13
	v_add_u32_e32 v12, v19, v0

.LBB0_1153:
	s_andn2_b64 vcc, exec, s[14:15]
	s_cbranch_vccnz .LBB0_1168
	s_add_u32 s2, s12, 0x1000
	s_addc_u32 s3, s13, 0
	s_waitcnt lgkmcnt(0)
	global_load_dword v239, v1, s[2:3] sc1
	s_mov_b32 s10, 0
	s_sleep 12
.Lsb_loop:
	global_load_dword v248, v1, s[2:3] sc1
	s_waitcnt vmcnt(1)
	v_cmp_ge_u32_e32 vcc, v239, v0
	s_cbranch_vccnz .Lsb_done
	global_load_dword v239, v1, s[2:3] sc1
	s_waitcnt vmcnt(1)
	v_cmp_ge_u32_e32 vcc, v248, v0
	s_cbranch_vccnz .Lsb_done
	s_add_i32 s10, s10, 1
	s_cmp_lt_u32 s10, 0x40000
	s_cbranch_scc1 .Lsb_loop
.Lsb_done:
.LBB0_1168:
	s_or_b64 exec, exec, s[0:1]
	s_waitcnt lgkmcnt(0)
	s_barrier
	s_getpc_b64 s[98:99]
